# ffn_up k-loop: A fragments triple-buffered, B fragments of k-step 1 prefetched (two share registers)
# speedup vs baseline: 1.0581x; 1.0216x over previous
; template <int MI, int NJ> ...
;     ...
;   for (int kt = 0; kt < nk; ++kt) {
;     const int buf = kt & 1;
;     {
;       G8STORE(buf ^ 1);
;       const u16* ga_ = (kt + 2 < nk) ? Ag + (kt + 2) * 64 : Ag + nAoff;
;       const u16* gb_ = (kt + 2 < nk) ? Bg + (kt + 2) * 64 : Bg + nBoff;
;       G8LOADP(ga_, gb_);
;     }
;     __builtin_amdgcn_sched_barrier(0);
;     __builtin_amdgcn_s_setprio(1);
;     const u16* a = ra_ + buf * AROWS * 64;
;     const u16* b = rb_ + buf * BROWS * 64;
; #pragma unroll
;     for (int ks = 0; ks < 2; ++ks) {
;       const u16* a_ = ks ? a + dsw : a;
;       const u16* b_ = ks ? b + dsw : b;
;       bf16x8 bfr[NJ];
; #pragma unroll
;       for (int j = 0; j < NJ; ++j) bfr[j] = *(const bf16x8*)(b_ + j * 16 * 64);
; #pragma unroll
;       for (int ih = 0; ih < MI / 4; ++ih) {
;         bf16x8 af[4];
; #pragma unroll
;         for (int i = 0; i < 4; ++i) af[i] = *(const bf16x8*)(a_ + (ih * 4 + i) * 16 * 64);
; #pragma unroll
;         for (int i = 0; i < 4; ++i)
; #pragma unroll
;           for (int j = 0; j < NJ; ++j) acc[ih * 4 + i][j] = mfma16(af[i], bfr[j], acc[ih * 4 + i][j]);
;       }
;     }
;     __builtin_amdgcn_s_setprio(0);
;     __builtin_amdgcn_sched_barrier(0);
;     __syncthreads();
;   }
; __device__ __forceinline__ void phase_ffn_up(const Params& p, const u16* Wgu, u16* smem, volatile LAS unsigned* vb_) {
;     ...
;     gemm8<8, 4>(acc, G8REGS_ARGS, pre, H, 1024, Wgu, 1024, 0, 1024, mt * 256, nt * 256,
;                 ((vb & 7) * 8 + (ltn & 7)) * 256, (ltn >> 3) * 256, 0, smem, tid);
.LBB0_601:
	s_and_b32 s48, s42, 0x4000
	s_xor_b32 s44, s48, 0x4000
	s_lshl_b32 s44, s44, 1
	s_cmp_lt_u32 s43, 14
	v_add_u32_e32 v208, s44, v185
	v_add_u32_e32 v209, s44, v186
	s_cselect_b32 s45, s23, s13
	s_cselect_b32 s44, s22, s12
	s_waitcnt vmcnt(5)
	ds_write_b128 v208, v[2:5]
	ds_write_b128 v208, v[6:9] offset:8192
	s_waitcnt vmcnt(4)
	ds_write_b128 v208, v[10:13] offset:16384
	s_waitcnt vmcnt(3)
	ds_write_b128 v208, v[18:21] offset:24576
	ds_write_b128 v209, v[14:17]
	s_waitcnt vmcnt(2)
	ds_write_b128 v209, v[22:25] offset:8192
	s_waitcnt vmcnt(1)
	ds_write_b128 v209, v[26:29] offset:16384
	s_waitcnt vmcnt(0)
	ds_write_b128 v209, v[30:33] offset:24576
	v_lshl_add_u64 v[2:3], s[44:45], 1, v[170:171]
	v_add_co_u32_e32 v8, vcc, s15, v2
	s_cselect_b32 s47, s23, s21
	s_nop 0
	v_addc_co_u32_e32 v9, vcc, 0, v3, vcc
	v_add_co_u32_e32 v10, vcc, s14, v2
	s_cselect_b32 s46, s22, s20
	s_nop 0
	v_addc_co_u32_e32 v11, vcc, 0, v3, vcc
	v_add_co_u32_e32 v18, vcc, s54, v2
	v_lshl_add_u64 v[6:7], s[46:47], 1, v[172:173]
	s_nop 0
	v_addc_co_u32_e32 v19, vcc, 0, v3, vcc
	v_add_co_u32_e32 v22, vcc, s15, v6
	global_load_dwordx4 v[2:5], v[2:3], off
	s_nop 0
	global_load_dwordx4 v[14:17], v[6:7], off
	v_addc_co_u32_e32 v23, vcc, 0, v7, vcc
	v_add_co_u32_e32 v26, vcc, s14, v6
	s_nop 1
	v_addc_co_u32_e32 v27, vcc, 0, v7, vcc
	v_add_co_u32_e32 v30, vcc, s54, v6
	s_nop 1
	v_addc_co_u32_e32 v31, vcc, 0, v7, vcc
	global_load_dwordx4 v[6:9], v[8:9], off
	s_nop 0
	global_load_dwordx4 v[10:13], v[10:11], off
	s_nop 0
	global_load_dwordx4 v[18:21], v[18:19], off
	s_nop 0
	global_load_dwordx4 v[22:25], v[22:23], off
	s_nop 0
	global_load_dwordx4 v[26:29], v[26:27], off
	s_nop 0
	global_load_dwordx4 v[30:33], v[30:31], off
	s_setprio 1
	s_lshl_b32 s44, s48, 1
	v_add_u32_e32 v228, s44, v187
	v_add_u32_e32 v229, s44, v188
	ds_read_b128 v[212:215], v229
	ds_read_b128 v[208:211], v228
	ds_read_b128 v[216:219], v229 offset:2048
	ds_read_b128 v[220:223], v229 offset:4096
	ds_read_b128 v[224:227], v229 offset:6144
	ds_read_b128 v[234:237], v228 offset:2048
	ds_read_b128 v[238:241], v228 offset:4096
	v_add_u32_e32 v229, v229, v196
	s_waitcnt lgkmcnt(5)
	v_mfma_f32_16x16x32_bf16 v[158:161], v[208:211], v[212:215], v[158:161]
	s_waitcnt lgkmcnt(4)
	v_mfma_f32_16x16x32_bf16 v[154:157], v[208:211], v[216:219], v[154:157]
	s_waitcnt lgkmcnt(3)
	v_mfma_f32_16x16x32_bf16 v[150:153], v[208:211], v[220:223], v[150:153]
	s_waitcnt lgkmcnt(2)
	v_mfma_f32_16x16x32_bf16 v[146:149], v[208:211], v[224:227], v[146:149]
	ds_read_b128 v[208:211], v228 offset:6144
	s_waitcnt lgkmcnt(2)
	v_mfma_f32_16x16x32_bf16 v[142:145], v[234:237], v[212:215], v[142:145]
	v_mfma_f32_16x16x32_bf16 v[138:141], v[234:237], v[216:219], v[138:141]
	v_mfma_f32_16x16x32_bf16 v[134:137], v[234:237], v[220:223], v[134:137]
	v_mfma_f32_16x16x32_bf16 v[130:133], v[234:237], v[224:227], v[130:133]
	ds_read_b128 v[234:237], v228 offset:8192
	s_waitcnt lgkmcnt(2)
	v_mfma_f32_16x16x32_bf16 v[126:129], v[238:241], v[212:215], v[126:129]
	v_mfma_f32_16x16x32_bf16 v[122:125], v[238:241], v[216:219], v[122:125]
	v_mfma_f32_16x16x32_bf16 v[118:121], v[238:241], v[220:223], v[118:121]
	v_mfma_f32_16x16x32_bf16 v[114:117], v[238:241], v[224:227], v[114:117]
	ds_read_b128 v[238:241], v228 offset:10240
	ds_read_b128 v[242:245], v229
	s_waitcnt lgkmcnt(3)
	v_mfma_f32_16x16x32_bf16 v[110:113], v[208:211], v[212:215], v[110:113]
	v_mfma_f32_16x16x32_bf16 v[106:109], v[208:211], v[216:219], v[106:109]
	v_mfma_f32_16x16x32_bf16 v[102:105], v[208:211], v[220:223], v[102:105]
	v_mfma_f32_16x16x32_bf16 v[98:101], v[208:211], v[224:227], v[98:101]
	ds_read_b128 v[208:211], v228 offset:12288
	ds_read_b128 v[246:249], v229 offset:2048
	s_waitcnt lgkmcnt(4)
	v_mfma_f32_16x16x32_bf16 v[94:97], v[234:237], v[212:215], v[94:97]
	v_mfma_f32_16x16x32_bf16 v[90:93], v[234:237], v[216:219], v[90:93]
	v_mfma_f32_16x16x32_bf16 v[86:89], v[234:237], v[220:223], v[86:89]
	v_mfma_f32_16x16x32_bf16 v[82:85], v[234:237], v[224:227], v[82:85]
	ds_read_b128 v[234:237], v228 offset:14336
	s_waitcnt lgkmcnt(4)
	v_mfma_f32_16x16x32_bf16 v[78:81], v[238:241], v[212:215], v[78:81]
	v_mfma_f32_16x16x32_bf16 v[74:77], v[238:241], v[216:219], v[74:77]
	v_mfma_f32_16x16x32_bf16 v[70:73], v[238:241], v[220:223], v[70:73]
	v_mfma_f32_16x16x32_bf16 v[66:69], v[238:241], v[224:227], v[66:69]
	v_add_u32_e32 v228, v228, v196
	ds_read_b128 v[238:241], v228
	s_waitcnt lgkmcnt(3)
	v_mfma_f32_16x16x32_bf16 v[62:65], v[208:211], v[212:215], v[62:65]
	v_mfma_f32_16x16x32_bf16 v[58:61], v[208:211], v[216:219], v[58:61]
	v_mfma_f32_16x16x32_bf16 v[54:57], v[208:211], v[220:223], v[54:57]
	v_mfma_f32_16x16x32_bf16 v[50:53], v[208:211], v[224:227], v[50:53]
	ds_read_b128 v[208:211], v228 offset:2048
	s_waitcnt lgkmcnt(2)
	v_mfma_f32_16x16x32_bf16 v[38:41], v[234:237], v[220:223], v[38:41]
	v_mfma_f32_16x16x32_bf16 v[34:37], v[234:237], v[224:227], v[34:37]
	ds_read_b128 v[220:223], v229 offset:4096
	ds_read_b128 v[224:227], v229 offset:6144
	v_mfma_f32_16x16x32_bf16 v[46:49], v[234:237], v[212:215], v[46:49]
	v_mfma_f32_16x16x32_bf16 v[42:45], v[234:237], v[216:219], v[42:45]
	ds_read_b128 v[234:237], v228 offset:4096
	s_waitcnt lgkmcnt(4)
	v_mfma_f32_16x16x32_bf16 v[158:161], v[238:241], v[242:245], v[158:161]
	v_mfma_f32_16x16x32_bf16 v[154:157], v[238:241], v[246:249], v[154:157]
	s_waitcnt lgkmcnt(1)
	v_mfma_f32_16x16x32_bf16 v[150:153], v[238:241], v[220:223], v[150:153]
	v_mfma_f32_16x16x32_bf16 v[146:149], v[238:241], v[224:227], v[146:149]
	ds_read_b128 v[238:241], v228 offset:6144
	s_waitcnt lgkmcnt(4)
; __device__ __forceinline__ float siluf_(float x) { return x / (1.0f + __expf(-x)); }
; template <int MI, int NJ> ...
;     ...
;     for (int ks = 0; ks < 2; ++ks) {
;       const u16* a_ = ks ? a + dsw : a;
;       const u16* b_ = ks ? b + dsw : b;
;       bf16x8 bfr[NJ];
; #pragma unroll
;       for (int j = 0; j < NJ; ++j) bfr[j] = *(const bf16x8*)(b_ + j * 16 * 64);
; #pragma unroll
;       for (int ih = 0; ih < MI / 4; ++ih) {
;         bf16x8 af[4];
; #pragma unroll
;         for (int i = 0; i < 4; ++i) af[i] = *(const bf16x8*)(a_ + (ih * 4 + i) * 16 * 64);
; #pragma unroll
;         for (int i = 0; i < 4; ++i)
; #pragma unroll
;           for (int j = 0; j < NJ; ++j) acc[ih * 4 + i][j] = mfma16(af[i], bfr[j], acc[ih * 4 + i][j]);
;       }
; __device__ __forceinline__ void phase_ffn_up(const Params& p, const u16* Wgu, u16* smem, volatile LAS unsigned* vb_) {
;     ...
;           const float g = acc[i][2 * jp][r], u = acc[i][2 * jp + 1][r];
;           smem[(wm * 128 + i * 16 + (lane >> 4) * 4 + r) * 136 + (wn * 2 + jp) * 16 + (lane & 15)] = f2bf(siluf_(g) * u);
	v_mfma_f32_16x16x32_bf16 v[142:145], v[208:211], v[242:245], v[142:145]
	v_mfma_f32_16x16x32_bf16 v[138:141], v[208:211], v[246:249], v[138:141]
	v_mfma_f32_16x16x32_bf16 v[134:137], v[208:211], v[220:223], v[134:137]
	v_mfma_f32_16x16x32_bf16 v[130:133], v[208:211], v[224:227], v[130:133]
	ds_read_b128 v[208:211], v228 offset:8192
	s_waitcnt lgkmcnt(2)
	v_mfma_f32_16x16x32_bf16 v[126:129], v[234:237], v[242:245], v[126:129]
	v_mfma_f32_16x16x32_bf16 v[122:125], v[234:237], v[246:249], v[122:125]
	v_mfma_f32_16x16x32_bf16 v[118:121], v[234:237], v[220:223], v[118:121]
	v_mfma_f32_16x16x32_bf16 v[114:117], v[234:237], v[224:227], v[114:117]
	ds_read_b128 v[234:237], v228 offset:10240
	s_waitcnt lgkmcnt(2)
	v_mfma_f32_16x16x32_bf16 v[110:113], v[238:241], v[242:245], v[110:113]
	v_mfma_f32_16x16x32_bf16 v[106:109], v[238:241], v[246:249], v[106:109]
	v_mfma_f32_16x16x32_bf16 v[102:105], v[238:241], v[220:223], v[102:105]
	v_mfma_f32_16x16x32_bf16 v[98:101], v[238:241], v[224:227], v[98:101]
	ds_read_b128 v[238:241], v228 offset:12288
	s_waitcnt lgkmcnt(2)
	v_mfma_f32_16x16x32_bf16 v[94:97], v[208:211], v[242:245], v[94:97]
	v_mfma_f32_16x16x32_bf16 v[90:93], v[208:211], v[246:249], v[90:93]
	v_mfma_f32_16x16x32_bf16 v[86:89], v[208:211], v[220:223], v[86:89]
	v_mfma_f32_16x16x32_bf16 v[82:85], v[208:211], v[224:227], v[82:85]
	ds_read_b128 v[208:211], v228 offset:14336
	s_waitcnt lgkmcnt(2)
	v_mfma_f32_16x16x32_bf16 v[78:81], v[234:237], v[242:245], v[78:81]
	v_mfma_f32_16x16x32_bf16 v[74:77], v[234:237], v[246:249], v[74:77]
	v_mfma_f32_16x16x32_bf16 v[70:73], v[234:237], v[220:223], v[70:73]
	v_mfma_f32_16x16x32_bf16 v[66:69], v[234:237], v[224:227], v[66:69]
	s_waitcnt lgkmcnt(1)
	v_mfma_f32_16x16x32_bf16 v[62:65], v[238:241], v[242:245], v[62:65]
	v_mfma_f32_16x16x32_bf16 v[58:61], v[238:241], v[246:249], v[58:61]
	v_mfma_f32_16x16x32_bf16 v[54:57], v[238:241], v[220:223], v[54:57]
	v_mfma_f32_16x16x32_bf16 v[50:53], v[238:241], v[224:227], v[50:53]
	s_waitcnt lgkmcnt(0)
	v_mfma_f32_16x16x32_bf16 v[46:49], v[208:211], v[242:245], v[46:49]
	v_mfma_f32_16x16x32_bf16 v[42:45], v[208:211], v[246:249], v[42:45]
	v_mfma_f32_16x16x32_bf16 v[38:41], v[208:211], v[220:223], v[38:41]
	v_mfma_f32_16x16x32_bf16 v[34:37], v[208:211], v[224:227], v[34:37]
	s_setprio 0
	s_add_i32 s43, s43, 1
	s_add_u32 s22, s22, 64
	s_addc_u32 s23, s23, 0
	s_addk_i32 s42, 0x4000
	s_cmpk_lg_i32 s22, 0x480
	s_barrier
	s_cbranch_scc1 .LBB0_601
	v_mul_f32_e32 v170, 0xbfb8aa3b, v158
	v_exp_f32_e32 v170, v170
	s_nop 0
	v_add_f32_e32 v170, 1.0, v170
	v_div_scale_f32 v171, s[12:13], v170, v170, v158
	v_rcp_f32_e32 v172, v171
	s_nop 0
	v_fma_f32 v173, -v171, v172, 1.0
	v_fmac_f32_e32 v172, v173, v172
	v_div_scale_f32 v173, vcc, v158, v170, v158
	v_mul_f32_e32 v208, v173, v172
	v_fma_f32 v209, -v171, v208, v173
	v_fmac_f32_e32 v208, v209, v172
	v_fma_f32 v171, -v171, v208, v173
	v_div_fmas_f32 v171, v171, v172, v208
	v_div_fixup_f32 v158, v171, v170, v158
	v_mul_f32_e32 v154, v154, v158
	v_cvt_pk_bf16_f32 v154, v154, s0
	ds_write_b16 v168, v154
	v_mul_f32_e32 v154, 0xbfb8aa3b, v159
	v_exp_f32_e32 v154, v154
	s_nop 0
	v_add_f32_e32 v154, 1.0, v154
	v_div_scale_f32 v158, s[12:13], v154, v154, v159
	v_rcp_f32_e32 v170, v158
	s_nop 0
	v_fma_f32 v171, -v158, v170, 1.0
	v_fmac_f32_e32 v170, v171, v170
	v_div_scale_f32 v171, vcc, v159, v154, v159
	v_mul_f32_e32 v172, v171, v170
	v_fma_f32 v173, -v158, v172, v171
	v_fmac_f32_e32 v172, v173, v170
	v_fma_f32 v158, -v158, v172, v171
	v_div_fmas_f32 v158, v158, v170, v172
	v_div_fixup_f32 v154, v158, v154, v159
	v_mul_f32_e32 v154, v155, v154
	v_cvt_pk_bf16_f32 v154, v154, s0
	ds_write_b16 v168, v154 offset:272
	v_mul_f32_e32 v154, 0xbfb8aa3b, v160
	v_exp_f32_e32 v154, v154
	s_nop 0
	v_add_f32_e32 v154, 1.0, v154
	v_div_scale_f32 v155, s[12:13], v154, v154, v160
	v_rcp_f32_e32 v158, v155
	s_nop 0
	v_fma_f32 v159, -v155, v158, 1.0
	v_fmac_f32_e32 v158, v159, v158
	v_div_scale_f32 v159, vcc, v160, v154, v160
	v_mul_f32_e32 v170, v159, v158
	v_fma_f32 v171, -v155, v170, v159
	v_fmac_f32_e32 v170, v171, v158
	v_fma_f32 v155, -v155, v170, v159
	v_div_fmas_f32 v155, v155, v158, v170
	v_div_fixup_f32 v154, v155, v154, v160
	v_mul_f32_e32 v154, v156, v154
	v_cvt_pk_bf16_f32 v154, v154, s0
	ds_write_b16 v168, v154 offset:544
	v_mul_f32_e32 v154, 0xbfb8aa3b, v161
	v_exp_f32_e32 v154, v154
	s_nop 0
	v_add_f32_e32 v154, 1.0, v154
	v_div_scale_f32 v155, s[12:13], v154, v154, v161
	v_rcp_f32_e32 v156, v155
	s_nop 0
	v_fma_f32 v158, -v155, v156, 1.0
	v_fmac_f32_e32 v156, v158, v156
	v_div_scale_f32 v158, vcc, v161, v154, v161
	v_mul_f32_e32 v159, v158, v156
	v_fma_f32 v160, -v155, v159, v158
	v_fmac_f32_e32 v159, v160, v156
	v_fma_f32 v155, -v155, v159, v158
	v_div_fmas_f32 v155, v155, v156, v159
	v_div_fixup_f32 v154, v155, v154, v161
	v_mul_f32_e32 v154, v157, v154
	v_cvt_pk_bf16_f32 v154, v154, s0
	ds_write_b16 v168, v154 offset:816
	v_mul_f32_e32 v154, 0xbfb8aa3b, v150
	v_exp_f32_e32 v154, v154
	s_nop 0
	v_add_f32_e32 v154, 1.0, v154
	v_div_scale_f32 v155, s[12:13], v154, v154, v150
	v_rcp_f32_e32 v156, v155
	s_nop 0
	v_fma_f32 v157, -v155, v156, 1.0
	v_fmac_f32_e32 v156, v157, v156
	v_div_scale_f32 v157, vcc, v150, v154, v150
	v_mul_f32_e32 v158, v157, v156
	v_fma_f32 v159, -v155, v158, v157
	v_fmac_f32_e32 v158, v159, v156
	v_fma_f32 v155, -v155, v158, v157
	v_div_fmas_f32 v155, v155, v156, v158
	v_div_fixup_f32 v150, v155, v154, v150
	v_mul_f32_e32 v146, v146, v150
	v_cvt_pk_bf16_f32 v146, v146, s0
	ds_write_b16 v168, v146 offset:32
	v_mul_f32_e32 v146, 0xbfb8aa3b, v151
	v_exp_f32_e32 v146, v146
	s_nop 0
	v_add_f32_e32 v146, 1.0, v146
; __device__ __forceinline__ float siluf_(float x) { return x / (1.0f + __expf(-x)); }
; __device__ __forceinline__ void phase_ffn_up(const Params& p, const u16* Wgu, u16* smem, volatile LAS unsigned* vb_) {
;     ...
;     for (int i = 0; i < 8; ++i)
; #pragma unroll
;       for (int jp = 0; jp < 2; ++jp) {
; #pragma unroll
;         for (int r = 0; r < 4; ++r) {
;           const float g = acc[i][2 * jp][r], u = acc[i][2 * jp + 1][r];
;           smem[(wm * 128 + i * 16 + (lane >> 4) * 4 + r) * 136 + (wn * 2 + jp) * 16 + (lane & 15)] = f2bf(siluf_(g) * u);
;         }
;         __builtin_amdgcn_sched_barrier(0);
;       }
	v_div_scale_f32 v150, s[12:13], v146, v146, v151
	v_rcp_f32_e32 v154, v150
	s_nop 0
	v_fma_f32 v155, -v150, v154, 1.0
	v_fmac_f32_e32 v154, v155, v154
	v_div_scale_f32 v155, vcc, v151, v146, v151
	v_mul_f32_e32 v156, v155, v154
	v_fma_f32 v157, -v150, v156, v155
	v_fmac_f32_e32 v156, v157, v154
	v_fma_f32 v150, -v150, v156, v155
	v_div_fmas_f32 v150, v150, v154, v156
	v_div_fixup_f32 v146, v150, v146, v151
	v_mul_f32_e32 v146, v147, v146
	v_cvt_pk_bf16_f32 v146, v146, s0
	ds_write_b16 v168, v146 offset:304
	v_mul_f32_e32 v146, 0xbfb8aa3b, v152
	v_exp_f32_e32 v146, v146
	s_nop 0
	v_add_f32_e32 v146, 1.0, v146
	v_div_scale_f32 v147, s[12:13], v146, v146, v152
	v_rcp_f32_e32 v150, v147
	s_nop 0
	v_fma_f32 v151, -v147, v150, 1.0
	v_fmac_f32_e32 v150, v151, v150
	v_div_scale_f32 v151, vcc, v152, v146, v152
	v_mul_f32_e32 v154, v151, v150
	v_fma_f32 v155, -v147, v154, v151
	v_fmac_f32_e32 v154, v155, v150
	v_fma_f32 v147, -v147, v154, v151
	v_div_fmas_f32 v147, v147, v150, v154
	v_div_fixup_f32 v146, v147, v146, v152
	v_mul_f32_e32 v146, v148, v146
	v_cvt_pk_bf16_f32 v146, v146, s0
	ds_write_b16 v168, v146 offset:576
	v_mul_f32_e32 v146, 0xbfb8aa3b, v153
	v_exp_f32_e32 v146, v146
	s_nop 0
	v_add_f32_e32 v146, 1.0, v146
	v_div_scale_f32 v147, s[12:13], v146, v146, v153
	v_rcp_f32_e32 v148, v147
	s_nop 0
	v_fma_f32 v150, -v147, v148, 1.0
	v_fmac_f32_e32 v148, v150, v148
	v_div_scale_f32 v150, vcc, v153, v146, v153
	v_mul_f32_e32 v151, v150, v148
	v_fma_f32 v152, -v147, v151, v150
	v_fmac_f32_e32 v151, v152, v148
	v_fma_f32 v147, -v147, v151, v150
	v_div_fmas_f32 v147, v147, v148, v151
	v_div_fixup_f32 v146, v147, v146, v153
	v_mul_f32_e32 v146, v149, v146
	v_cvt_pk_bf16_f32 v146, v146, s0
	ds_write_b16 v168, v146 offset:848
	v_mul_f32_e32 v146, 0xbfb8aa3b, v142
	v_exp_f32_e32 v146, v146
	s_nop 0
	v_add_f32_e32 v146, 1.0, v146
	v_div_scale_f32 v147, s[12:13], v146, v146, v142
	v_rcp_f32_e32 v148, v147
	s_nop 0
	v_fma_f32 v149, -v147, v148, 1.0
	v_fmac_f32_e32 v148, v149, v148
	v_div_scale_f32 v149, vcc, v142, v146, v142
	v_mul_f32_e32 v150, v149, v148
	v_fma_f32 v151, -v147, v150, v149
	v_fmac_f32_e32 v150, v151, v148
	v_fma_f32 v147, -v147, v150, v149
	v_div_fmas_f32 v147, v147, v148, v150
	v_div_fixup_f32 v142, v147, v146, v142
	v_mul_f32_e32 v138, v138, v142
	v_cvt_pk_bf16_f32 v138, v138, s0
	ds_write_b16 v168, v138 offset:4352
	v_mul_f32_e32 v138, 0xbfb8aa3b, v143
	v_exp_f32_e32 v138, v138
	s_nop 0
	v_add_f32_e32 v138, 1.0, v138
	v_div_scale_f32 v142, s[12:13], v138, v138, v143
	v_rcp_f32_e32 v146, v142
	s_nop 0
	v_fma_f32 v147, -v142, v146, 1.0
	v_fmac_f32_e32 v146, v147, v146
	v_div_scale_f32 v147, vcc, v143, v138, v143
	v_mul_f32_e32 v148, v147, v146
	v_fma_f32 v149, -v142, v148, v147
	v_fmac_f32_e32 v148, v149, v146
	v_fma_f32 v142, -v142, v148, v147
	v_div_fmas_f32 v142, v142, v146, v148
	v_div_fixup_f32 v138, v142, v138, v143
	v_mul_f32_e32 v138, v139, v138
	v_cvt_pk_bf16_f32 v138, v138, s0
	ds_write_b16 v168, v138 offset:4624
	v_mul_f32_e32 v138, 0xbfb8aa3b, v144
	v_exp_f32_e32 v138, v138
	s_nop 0
	v_add_f32_e32 v138, 1.0, v138
	v_div_scale_f32 v139, s[12:13], v138, v138, v144
	v_rcp_f32_e32 v142, v139
	s_nop 0
	v_fma_f32 v143, -v139, v142, 1.0
	v_fmac_f32_e32 v142, v143, v142
	v_div_scale_f32 v143, vcc, v144, v138, v144
	v_mul_f32_e32 v146, v143, v142
	v_fma_f32 v147, -v139, v146, v143
	v_fmac_f32_e32 v146, v147, v142
	v_fma_f32 v139, -v139, v146, v143
	v_div_fmas_f32 v139, v139, v142, v146
	v_div_fixup_f32 v138, v139, v138, v144
	v_mul_f32_e32 v138, v140, v138
	v_cvt_pk_bf16_f32 v138, v138, s0
	ds_write_b16 v168, v138 offset:4896
	v_mul_f32_e32 v138, 0xbfb8aa3b, v145
	v_exp_f32_e32 v138, v138
	s_nop 0
	v_add_f32_e32 v138, 1.0, v138
	v_div_scale_f32 v139, s[12:13], v138, v138, v145
	v_rcp_f32_e32 v140, v139
	s_nop 0
	v_fma_f32 v142, -v139, v140, 1.0
	v_fmac_f32_e32 v140, v142, v140
	v_div_scale_f32 v142, vcc, v145, v138, v145
	v_mul_f32_e32 v143, v142, v140
	v_fma_f32 v144, -v139, v143, v142
	v_fmac_f32_e32 v143, v144, v140
	v_fma_f32 v139, -v139, v143, v142
	v_div_fmas_f32 v139, v139, v140, v143
	v_div_fixup_f32 v138, v139, v138, v145
	v_mul_f32_e32 v138, v141, v138
	v_cvt_pk_bf16_f32 v138, v138, s0
	ds_write_b16 v168, v138 offset:5168
	v_mul_f32_e32 v138, 0xbfb8aa3b, v134
	v_exp_f32_e32 v138, v138
	s_nop 0
	v_add_f32_e32 v138, 1.0, v138
	v_div_scale_f32 v139, s[12:13], v138, v138, v134
	v_rcp_f32_e32 v140, v139
	s_nop 0
	v_fma_f32 v141, -v139, v140, 1.0
	v_fmac_f32_e32 v140, v141, v140
	v_div_scale_f32 v141, vcc, v134, v138, v134
	v_mul_f32_e32 v142, v141, v140
	v_fma_f32 v143, -v139, v142, v141
	v_fmac_f32_e32 v142, v143, v140
	v_fma_f32 v139, -v139, v142, v141
	v_div_fmas_f32 v139, v139, v140, v142
	v_div_fixup_f32 v134, v139, v138, v134
	v_mul_f32_e32 v130, v130, v134
	v_cvt_pk_bf16_f32 v130, v130, s0
	ds_write_b16 v168, v130 offset:4384
	v_mul_f32_e32 v130, 0xbfb8aa3b, v135
	v_exp_f32_e32 v130, v130
	s_nop 0
	v_add_f32_e32 v130, 1.0, v130
	v_div_scale_f32 v134, s[12:13], v130, v130, v135
	v_rcp_f32_e32 v138, v134
	s_nop 0
	v_fma_f32 v139, -v134, v138, 1.0
	v_fmac_f32_e32 v138, v139, v138
	v_div_scale_f32 v139, vcc, v135, v130, v135
	v_mul_f32_e32 v140, v139, v138
	v_fma_f32 v141, -v134, v140, v139
	v_fmac_f32_e32 v140, v141, v138
	v_fma_f32 v134, -v134, v140, v139
	v_div_fmas_f32 v134, v134, v138, v140
	v_div_fixup_f32 v130, v134, v130, v135
	v_mul_f32_e32 v130, v131, v130
	v_cvt_pk_bf16_f32 v130, v130, s0
	ds_write_b16 v168, v130 offset:4656
	v_mul_f32_e32 v130, 0xbfb8aa3b, v136
	v_exp_f32_e32 v130, v130
	s_nop 0
	v_add_f32_e32 v130, 1.0, v130
	v_div_scale_f32 v131, s[12:13], v130, v130, v136
	v_rcp_f32_e32 v134, v131
	s_nop 0
; __device__ __forceinline__ float siluf_(float x) { return x / (1.0f + __expf(-x)); }
; __device__ __forceinline__ void phase_ffn_up(const Params& p, const u16* Wgu, u16* smem, volatile LAS unsigned* vb_) {
;     ...
;     for (int i = 0; i < 8; ++i)
; #pragma unroll
;       for (int jp = 0; jp < 2; ++jp) {
; #pragma unroll
;         for (int r = 0; r < 4; ++r) {
;           const float g = acc[i][2 * jp][r], u = acc[i][2 * jp + 1][r];
;           smem[(wm * 128 + i * 16 + (lane >> 4) * 4 + r) * 136 + (wn * 2 + jp) * 16 + (lane & 15)] = f2bf(siluf_(g) * u);
;         }
;         __builtin_amdgcn_sched_barrier(0);
;       }
	v_fma_f32 v135, -v131, v134, 1.0
	v_fmac_f32_e32 v134, v135, v134
	v_div_scale_f32 v135, vcc, v136, v130, v136
	v_mul_f32_e32 v138, v135, v134
	v_fma_f32 v139, -v131, v138, v135
	v_fmac_f32_e32 v138, v139, v134
	v_fma_f32 v131, -v131, v138, v135
	v_div_fmas_f32 v131, v131, v134, v138
	v_div_fixup_f32 v130, v131, v130, v136
	v_mul_f32_e32 v130, v132, v130
	v_cvt_pk_bf16_f32 v130, v130, s0
	ds_write_b16 v168, v130 offset:4928
	v_mul_f32_e32 v130, 0xbfb8aa3b, v137
	v_exp_f32_e32 v130, v130
	s_nop 0
	v_add_f32_e32 v130, 1.0, v130
	v_div_scale_f32 v131, s[12:13], v130, v130, v137
	v_rcp_f32_e32 v132, v131
	s_nop 0
	v_fma_f32 v134, -v131, v132, 1.0
	v_fmac_f32_e32 v132, v134, v132
	v_div_scale_f32 v134, vcc, v137, v130, v137
	v_mul_f32_e32 v135, v134, v132
	v_fma_f32 v136, -v131, v135, v134
	v_fmac_f32_e32 v135, v136, v132
	v_fma_f32 v131, -v131, v135, v134
	v_div_fmas_f32 v131, v131, v132, v135
	v_div_fixup_f32 v130, v131, v130, v137
	v_mul_f32_e32 v130, v133, v130
	v_cvt_pk_bf16_f32 v130, v130, s0
	ds_write_b16 v168, v130 offset:5200
	v_mul_f32_e32 v130, 0xbfb8aa3b, v126
	v_exp_f32_e32 v130, v130
	s_nop 0
	v_add_f32_e32 v130, 1.0, v130
	v_div_scale_f32 v131, s[12:13], v130, v130, v126
	v_rcp_f32_e32 v132, v131
	s_nop 0
	v_fma_f32 v133, -v131, v132, 1.0
	v_fmac_f32_e32 v132, v133, v132
	v_div_scale_f32 v133, vcc, v126, v130, v126
	v_mul_f32_e32 v134, v133, v132
	v_fma_f32 v135, -v131, v134, v133
	v_fmac_f32_e32 v134, v135, v132
	v_fma_f32 v131, -v131, v134, v133
	v_div_fmas_f32 v131, v131, v132, v134
	v_div_fixup_f32 v126, v131, v130, v126
	v_mul_f32_e32 v122, v122, v126
	v_cvt_pk_bf16_f32 v122, v122, s0
	ds_write_b16 v168, v122 offset:8704
	v_mul_f32_e32 v122, 0xbfb8aa3b, v127
	v_exp_f32_e32 v122, v122
	s_nop 0
	v_add_f32_e32 v122, 1.0, v122
	v_div_scale_f32 v126, s[12:13], v122, v122, v127
	v_rcp_f32_e32 v130, v126
	s_nop 0
	v_fma_f32 v131, -v126, v130, 1.0
	v_fmac_f32_e32 v130, v131, v130
	v_div_scale_f32 v131, vcc, v127, v122, v127
	v_mul_f32_e32 v132, v131, v130
	v_fma_f32 v133, -v126, v132, v131
	v_fmac_f32_e32 v132, v133, v130
	v_fma_f32 v126, -v126, v132, v131
	v_div_fmas_f32 v126, v126, v130, v132
	v_div_fixup_f32 v122, v126, v122, v127
	v_mul_f32_e32 v122, v123, v122
	v_cvt_pk_bf16_f32 v122, v122, s0
	ds_write_b16 v168, v122 offset:8976
	v_mul_f32_e32 v122, 0xbfb8aa3b, v128
	v_exp_f32_e32 v122, v122
	s_nop 0
	v_add_f32_e32 v122, 1.0, v122
	v_div_scale_f32 v123, s[12:13], v122, v122, v128
	v_rcp_f32_e32 v126, v123
	s_nop 0
	v_fma_f32 v127, -v123, v126, 1.0
	v_fmac_f32_e32 v126, v127, v126
	v_div_scale_f32 v127, vcc, v128, v122, v128
	v_mul_f32_e32 v130, v127, v126
	v_fma_f32 v131, -v123, v130, v127
	v_fmac_f32_e32 v130, v131, v126
	v_fma_f32 v123, -v123, v130, v127
	v_div_fmas_f32 v123, v123, v126, v130
	v_div_fixup_f32 v122, v123, v122, v128
	v_mul_f32_e32 v122, v124, v122
	v_cvt_pk_bf16_f32 v122, v122, s0
	ds_write_b16 v168, v122 offset:9248
	v_mul_f32_e32 v122, 0xbfb8aa3b, v129
	v_exp_f32_e32 v122, v122
	s_nop 0
	v_add_f32_e32 v122, 1.0, v122
	v_div_scale_f32 v123, s[12:13], v122, v122, v129
	v_rcp_f32_e32 v124, v123
	s_nop 0
	v_fma_f32 v126, -v123, v124, 1.0
	v_fmac_f32_e32 v124, v126, v124
	v_div_scale_f32 v126, vcc, v129, v122, v129
	v_mul_f32_e32 v127, v126, v124
	v_fma_f32 v128, -v123, v127, v126
	v_fmac_f32_e32 v127, v128, v124
	v_fma_f32 v123, -v123, v127, v126
	v_div_fmas_f32 v123, v123, v124, v127
	v_div_fixup_f32 v122, v123, v122, v129
	v_mul_f32_e32 v122, v125, v122
	v_cvt_pk_bf16_f32 v122, v122, s0
	ds_write_b16 v168, v122 offset:9520
	v_mul_f32_e32 v122, 0xbfb8aa3b, v118
	v_exp_f32_e32 v122, v122
	s_nop 0
	v_add_f32_e32 v122, 1.0, v122
	v_div_scale_f32 v123, s[12:13], v122, v122, v118
	v_rcp_f32_e32 v124, v123
	s_nop 0
	v_fma_f32 v125, -v123, v124, 1.0
	v_fmac_f32_e32 v124, v125, v124
	v_div_scale_f32 v125, vcc, v118, v122, v118
	v_mul_f32_e32 v126, v125, v124
	v_fma_f32 v127, -v123, v126, v125
	v_fmac_f32_e32 v126, v127, v124
	v_fma_f32 v123, -v123, v126, v125
	v_div_fmas_f32 v123, v123, v124, v126
	v_div_fixup_f32 v118, v123, v122, v118
	v_mul_f32_e32 v114, v114, v118
	v_cvt_pk_bf16_f32 v114, v114, s0
	ds_write_b16 v168, v114 offset:8736
	v_mul_f32_e32 v114, 0xbfb8aa3b, v119
	v_exp_f32_e32 v114, v114
	s_nop 0
	v_add_f32_e32 v114, 1.0, v114
	v_div_scale_f32 v118, s[12:13], v114, v114, v119
	v_rcp_f32_e32 v122, v118
	s_nop 0
	v_fma_f32 v123, -v118, v122, 1.0
	v_fmac_f32_e32 v122, v123, v122
	v_div_scale_f32 v123, vcc, v119, v114, v119
	v_mul_f32_e32 v124, v123, v122
	v_fma_f32 v125, -v118, v124, v123
	v_fmac_f32_e32 v124, v125, v122
	v_fma_f32 v118, -v118, v124, v123
	v_div_fmas_f32 v118, v118, v122, v124
	v_div_fixup_f32 v114, v118, v114, v119
	v_mul_f32_e32 v114, v115, v114
	v_cvt_pk_bf16_f32 v114, v114, s0
	ds_write_b16 v168, v114 offset:9008
	v_mul_f32_e32 v114, 0xbfb8aa3b, v120
	v_exp_f32_e32 v114, v114
	s_nop 0
	v_add_f32_e32 v114, 1.0, v114
	v_div_scale_f32 v115, s[12:13], v114, v114, v120
	v_rcp_f32_e32 v118, v115
	s_nop 0
	v_fma_f32 v119, -v115, v118, 1.0
	v_fmac_f32_e32 v118, v119, v118
	v_div_scale_f32 v119, vcc, v120, v114, v120
	v_mul_f32_e32 v122, v119, v118
	v_fma_f32 v123, -v115, v122, v119
	v_fmac_f32_e32 v122, v123, v118
	v_fma_f32 v115, -v115, v122, v119
	v_div_fmas_f32 v115, v115, v118, v122
	v_div_fixup_f32 v114, v115, v114, v120
	v_mul_f32_e32 v114, v116, v114
	v_cvt_pk_bf16_f32 v114, v114, s0
	ds_write_b16 v168, v114 offset:9280
	v_mul_f32_e32 v114, 0xbfb8aa3b, v121
	v_exp_f32_e32 v114, v114
	s_nop 0
	v_add_f32_e32 v114, 1.0, v114
	v_div_scale_f32 v115, s[12:13], v114, v114, v121
	v_rcp_f32_e32 v116, v115
	s_nop 0
	v_fma_f32 v118, -v115, v116, 1.0
	v_fmac_f32_e32 v116, v118, v116
; __device__ __forceinline__ float siluf_(float x) { return x / (1.0f + __expf(-x)); }
; __device__ __forceinline__ void phase_ffn_up(const Params& p, const u16* Wgu, u16* smem, volatile LAS unsigned* vb_) {
;     ...
;     for (int i = 0; i < 8; ++i)
; #pragma unroll
;       for (int jp = 0; jp < 2; ++jp) {
; #pragma unroll
;         for (int r = 0; r < 4; ++r) {
;           const float g = acc[i][2 * jp][r], u = acc[i][2 * jp + 1][r];
;           smem[(wm * 128 + i * 16 + (lane >> 4) * 4 + r) * 136 + (wn * 2 + jp) * 16 + (lane & 15)] = f2bf(siluf_(g) * u);
;         }
;         __builtin_amdgcn_sched_barrier(0);
;       }
	v_div_scale_f32 v118, vcc, v121, v114, v121
	v_mul_f32_e32 v119, v118, v116
	v_fma_f32 v120, -v115, v119, v118
	v_fmac_f32_e32 v119, v120, v116
	v_fma_f32 v115, -v115, v119, v118
	v_div_fmas_f32 v115, v115, v116, v119
	v_div_fixup_f32 v114, v115, v114, v121
	v_mul_f32_e32 v114, v117, v114
	v_cvt_pk_bf16_f32 v114, v114, s0
	ds_write_b16 v168, v114 offset:9552
	v_mul_f32_e32 v114, 0xbfb8aa3b, v110
	v_exp_f32_e32 v114, v114
	s_nop 0
	v_add_f32_e32 v114, 1.0, v114
	v_div_scale_f32 v115, s[12:13], v114, v114, v110
	v_rcp_f32_e32 v116, v115
	s_nop 0
	v_fma_f32 v117, -v115, v116, 1.0
	v_fmac_f32_e32 v116, v117, v116
	v_div_scale_f32 v117, vcc, v110, v114, v110
	v_mul_f32_e32 v118, v117, v116
	v_fma_f32 v119, -v115, v118, v117
	v_fmac_f32_e32 v118, v119, v116
	v_fma_f32 v115, -v115, v118, v117
	v_div_fmas_f32 v115, v115, v116, v118
	v_div_fixup_f32 v110, v115, v114, v110
	v_mul_f32_e32 v106, v106, v110
	v_cvt_pk_bf16_f32 v106, v106, s0
	ds_write_b16 v168, v106 offset:13056
	v_mul_f32_e32 v106, 0xbfb8aa3b, v111
	v_exp_f32_e32 v106, v106
	s_nop 0
	v_add_f32_e32 v106, 1.0, v106
	v_div_scale_f32 v110, s[12:13], v106, v106, v111
	v_rcp_f32_e32 v114, v110
	s_nop 0
	v_fma_f32 v115, -v110, v114, 1.0
	v_fmac_f32_e32 v114, v115, v114
	v_div_scale_f32 v115, vcc, v111, v106, v111
	v_mul_f32_e32 v116, v115, v114
	v_fma_f32 v117, -v110, v116, v115
	v_fmac_f32_e32 v116, v117, v114
	v_fma_f32 v110, -v110, v116, v115
	v_div_fmas_f32 v110, v110, v114, v116
	v_div_fixup_f32 v106, v110, v106, v111
	v_mul_f32_e32 v106, v107, v106
	v_cvt_pk_bf16_f32 v106, v106, s0
	ds_write_b16 v168, v106 offset:13328
	v_mul_f32_e32 v106, 0xbfb8aa3b, v112
	v_exp_f32_e32 v106, v106
	s_nop 0
	v_add_f32_e32 v106, 1.0, v106
	v_div_scale_f32 v107, s[12:13], v106, v106, v112
	v_rcp_f32_e32 v110, v107
	s_nop 0
	v_fma_f32 v111, -v107, v110, 1.0
	v_fmac_f32_e32 v110, v111, v110
	v_div_scale_f32 v111, vcc, v112, v106, v112
	v_mul_f32_e32 v114, v111, v110
	v_fma_f32 v115, -v107, v114, v111
	v_fmac_f32_e32 v114, v115, v110
	v_fma_f32 v107, -v107, v114, v111
	v_div_fmas_f32 v107, v107, v110, v114
	v_div_fixup_f32 v106, v107, v106, v112
	v_mul_f32_e32 v106, v108, v106
	v_cvt_pk_bf16_f32 v106, v106, s0
	ds_write_b16 v168, v106 offset:13600
	v_mul_f32_e32 v106, 0xbfb8aa3b, v113
	v_exp_f32_e32 v106, v106
	s_nop 0
	v_add_f32_e32 v106, 1.0, v106
	v_div_scale_f32 v107, s[12:13], v106, v106, v113
	v_rcp_f32_e32 v108, v107
	s_nop 0
	v_fma_f32 v110, -v107, v108, 1.0
	v_fmac_f32_e32 v108, v110, v108
	v_div_scale_f32 v110, vcc, v113, v106, v113
	v_mul_f32_e32 v111, v110, v108
	v_fma_f32 v112, -v107, v111, v110
	v_fmac_f32_e32 v111, v112, v108
	v_fma_f32 v107, -v107, v111, v110
	v_div_fmas_f32 v107, v107, v108, v111
	v_div_fixup_f32 v106, v107, v106, v113
	v_mul_f32_e32 v106, v109, v106
	v_cvt_pk_bf16_f32 v106, v106, s0
	ds_write_b16 v168, v106 offset:13872
	v_mul_f32_e32 v106, 0xbfb8aa3b, v102
	v_exp_f32_e32 v106, v106
	s_nop 0
	v_add_f32_e32 v106, 1.0, v106
	v_div_scale_f32 v107, s[12:13], v106, v106, v102
	v_rcp_f32_e32 v108, v107
	s_nop 0
	v_fma_f32 v109, -v107, v108, 1.0
	v_fmac_f32_e32 v108, v109, v108
	v_div_scale_f32 v109, vcc, v102, v106, v102
	v_mul_f32_e32 v110, v109, v108
	v_fma_f32 v111, -v107, v110, v109
	v_fmac_f32_e32 v110, v111, v108
	v_fma_f32 v107, -v107, v110, v109
	v_div_fmas_f32 v107, v107, v108, v110
	v_div_fixup_f32 v102, v107, v106, v102
	v_mul_f32_e32 v98, v98, v102
	v_cvt_pk_bf16_f32 v98, v98, s0
	ds_write_b16 v168, v98 offset:13088
	v_mul_f32_e32 v98, 0xbfb8aa3b, v103
	v_exp_f32_e32 v98, v98
	s_nop 0
	v_add_f32_e32 v98, 1.0, v98
	v_div_scale_f32 v102, s[12:13], v98, v98, v103
	v_rcp_f32_e32 v106, v102
	s_nop 0
	v_fma_f32 v107, -v102, v106, 1.0
	v_fmac_f32_e32 v106, v107, v106
	v_div_scale_f32 v107, vcc, v103, v98, v103
	v_mul_f32_e32 v108, v107, v106
	v_fma_f32 v109, -v102, v108, v107
	v_fmac_f32_e32 v108, v109, v106
	v_fma_f32 v102, -v102, v108, v107
	v_div_fmas_f32 v102, v102, v106, v108
	v_div_fixup_f32 v98, v102, v98, v103
	v_mul_f32_e32 v98, v99, v98
	v_cvt_pk_bf16_f32 v98, v98, s0
	ds_write_b16 v168, v98 offset:13360
	v_mul_f32_e32 v98, 0xbfb8aa3b, v104
	v_exp_f32_e32 v98, v98
	s_nop 0
	v_add_f32_e32 v98, 1.0, v98
	v_div_scale_f32 v99, s[12:13], v98, v98, v104
	v_rcp_f32_e32 v102, v99
	s_nop 0
	v_fma_f32 v103, -v99, v102, 1.0
	v_fmac_f32_e32 v102, v103, v102
	v_div_scale_f32 v103, vcc, v104, v98, v104
	v_mul_f32_e32 v106, v103, v102
	v_fma_f32 v107, -v99, v106, v103
	v_fmac_f32_e32 v106, v107, v102
	v_fma_f32 v99, -v99, v106, v103
	v_div_fmas_f32 v99, v99, v102, v106
	v_div_fixup_f32 v98, v99, v98, v104
	v_mul_f32_e32 v98, v100, v98
	v_cvt_pk_bf16_f32 v98, v98, s0
	ds_write_b16 v168, v98 offset:13632
	v_mul_f32_e32 v98, 0xbfb8aa3b, v105
	v_exp_f32_e32 v98, v98
	s_nop 0
	v_add_f32_e32 v98, 1.0, v98
	v_div_scale_f32 v99, s[12:13], v98, v98, v105
	v_rcp_f32_e32 v100, v99
	s_nop 0
	v_fma_f32 v102, -v99, v100, 1.0
	v_fmac_f32_e32 v100, v102, v100
	v_div_scale_f32 v102, vcc, v105, v98, v105
	v_mul_f32_e32 v103, v102, v100
	v_fma_f32 v104, -v99, v103, v102
	v_fmac_f32_e32 v103, v104, v100
	v_fma_f32 v99, -v99, v103, v102
	v_div_fmas_f32 v99, v99, v100, v103
	v_div_fixup_f32 v98, v99, v98, v105
	v_mul_f32_e32 v98, v101, v98
	v_cvt_pk_bf16_f32 v98, v98, s0
	ds_write_b16 v168, v98 offset:13904
	v_mul_f32_e32 v98, 0xbfb8aa3b, v94
	v_exp_f32_e32 v98, v98
	s_nop 0
	v_add_f32_e32 v98, 1.0, v98
	v_div_scale_f32 v99, s[12:13], v98, v98, v94
	v_rcp_f32_e32 v100, v99
	s_nop 0
	v_fma_f32 v101, -v99, v100, 1.0
	v_fmac_f32_e32 v100, v101, v100
	v_div_scale_f32 v101, vcc, v94, v98, v94
	v_mul_f32_e32 v102, v101, v100
	v_fma_f32 v103, -v99, v102, v101
	v_fmac_f32_e32 v102, v103, v100
; __device__ __forceinline__ float siluf_(float x) { return x / (1.0f + __expf(-x)); }
; __device__ __forceinline__ void phase_ffn_up(const Params& p, const u16* Wgu, u16* smem, volatile LAS unsigned* vb_) {
;     ...
;     for (int i = 0; i < 8; ++i)
; #pragma unroll
;       for (int jp = 0; jp < 2; ++jp) {
; #pragma unroll
;         for (int r = 0; r < 4; ++r) {
;           const float g = acc[i][2 * jp][r], u = acc[i][2 * jp + 1][r];
;           smem[(wm * 128 + i * 16 + (lane >> 4) * 4 + r) * 136 + (wn * 2 + jp) * 16 + (lane & 15)] = f2bf(siluf_(g) * u);
;         }
;         __builtin_amdgcn_sched_barrier(0);
;       }
	v_fma_f32 v99, -v99, v102, v101
	v_div_fmas_f32 v99, v99, v100, v102
	v_div_fixup_f32 v94, v99, v98, v94
	v_mul_f32_e32 v90, v90, v94
	v_cvt_pk_bf16_f32 v90, v90, s0
	ds_write_b16 v168, v90 offset:17408
	v_mul_f32_e32 v90, 0xbfb8aa3b, v95
	v_exp_f32_e32 v90, v90
	s_nop 0
	v_add_f32_e32 v90, 1.0, v90
	v_div_scale_f32 v94, s[12:13], v90, v90, v95
	v_rcp_f32_e32 v98, v94
	s_nop 0
	v_fma_f32 v99, -v94, v98, 1.0
	v_fmac_f32_e32 v98, v99, v98
	v_div_scale_f32 v99, vcc, v95, v90, v95
	v_mul_f32_e32 v100, v99, v98
	v_fma_f32 v101, -v94, v100, v99
	v_fmac_f32_e32 v100, v101, v98
	v_fma_f32 v94, -v94, v100, v99
	v_div_fmas_f32 v94, v94, v98, v100
	v_div_fixup_f32 v90, v94, v90, v95
	v_mul_f32_e32 v90, v91, v90
	v_cvt_pk_bf16_f32 v90, v90, s0
	ds_write_b16 v168, v90 offset:17680
	v_mul_f32_e32 v90, 0xbfb8aa3b, v96
	v_exp_f32_e32 v90, v90
	s_nop 0
	v_add_f32_e32 v90, 1.0, v90
	v_div_scale_f32 v91, s[12:13], v90, v90, v96
	v_rcp_f32_e32 v94, v91
	s_nop 0
	v_fma_f32 v95, -v91, v94, 1.0
	v_fmac_f32_e32 v94, v95, v94
	v_div_scale_f32 v95, vcc, v96, v90, v96
	v_mul_f32_e32 v98, v95, v94
	v_fma_f32 v99, -v91, v98, v95
	v_fmac_f32_e32 v98, v99, v94
	v_fma_f32 v91, -v91, v98, v95
	v_div_fmas_f32 v91, v91, v94, v98
	v_div_fixup_f32 v90, v91, v90, v96
	v_mul_f32_e32 v90, v92, v90
	v_cvt_pk_bf16_f32 v90, v90, s0
	ds_write_b16 v168, v90 offset:17952
	v_mul_f32_e32 v90, 0xbfb8aa3b, v97
	v_exp_f32_e32 v90, v90
	s_nop 0
	v_add_f32_e32 v90, 1.0, v90
	v_div_scale_f32 v91, s[12:13], v90, v90, v97
	v_rcp_f32_e32 v92, v91
	s_nop 0
	v_fma_f32 v94, -v91, v92, 1.0
	v_fmac_f32_e32 v92, v94, v92
	v_div_scale_f32 v94, vcc, v97, v90, v97
	v_mul_f32_e32 v95, v94, v92
	v_fma_f32 v96, -v91, v95, v94
	v_fmac_f32_e32 v95, v96, v92
	v_fma_f32 v91, -v91, v95, v94
	v_div_fmas_f32 v91, v91, v92, v95
	v_div_fixup_f32 v90, v91, v90, v97
	v_mul_f32_e32 v90, v93, v90
	v_cvt_pk_bf16_f32 v90, v90, s0
	ds_write_b16 v168, v90 offset:18224
	v_mul_f32_e32 v90, 0xbfb8aa3b, v86
	v_exp_f32_e32 v90, v90
	s_nop 0
	v_add_f32_e32 v90, 1.0, v90
	v_div_scale_f32 v91, s[12:13], v90, v90, v86
	v_rcp_f32_e32 v92, v91
	s_nop 0
	v_fma_f32 v93, -v91, v92, 1.0
	v_fmac_f32_e32 v92, v93, v92
	v_div_scale_f32 v93, vcc, v86, v90, v86
	v_mul_f32_e32 v94, v93, v92
	v_fma_f32 v95, -v91, v94, v93
	v_fmac_f32_e32 v94, v95, v92
	v_fma_f32 v91, -v91, v94, v93
	v_div_fmas_f32 v91, v91, v92, v94
	v_div_fixup_f32 v86, v91, v90, v86
	v_mul_f32_e32 v82, v82, v86
	v_cvt_pk_bf16_f32 v82, v82, s0
	ds_write_b16 v168, v82 offset:17440
	v_mul_f32_e32 v82, 0xbfb8aa3b, v87
	v_exp_f32_e32 v82, v82
	s_nop 0
	v_add_f32_e32 v82, 1.0, v82
	v_div_scale_f32 v86, s[12:13], v82, v82, v87
	v_rcp_f32_e32 v90, v86
	s_nop 0
	v_fma_f32 v91, -v86, v90, 1.0
	v_fmac_f32_e32 v90, v91, v90
	v_div_scale_f32 v91, vcc, v87, v82, v87
	v_mul_f32_e32 v92, v91, v90
	v_fma_f32 v93, -v86, v92, v91
	v_fmac_f32_e32 v92, v93, v90
	v_fma_f32 v86, -v86, v92, v91
	v_div_fmas_f32 v86, v86, v90, v92
	v_div_fixup_f32 v82, v86, v82, v87
	v_mul_f32_e32 v82, v83, v82
	v_cvt_pk_bf16_f32 v82, v82, s0
	ds_write_b16 v168, v82 offset:17712
	v_mul_f32_e32 v82, 0xbfb8aa3b, v88
	v_exp_f32_e32 v82, v82
	s_nop 0
	v_add_f32_e32 v82, 1.0, v82
	v_div_scale_f32 v83, s[12:13], v82, v82, v88
	v_rcp_f32_e32 v86, v83
	s_nop 0
	v_fma_f32 v87, -v83, v86, 1.0
	v_fmac_f32_e32 v86, v87, v86
	v_div_scale_f32 v87, vcc, v88, v82, v88
	v_mul_f32_e32 v90, v87, v86
	v_fma_f32 v91, -v83, v90, v87
	v_fmac_f32_e32 v90, v91, v86
	v_fma_f32 v83, -v83, v90, v87
	v_div_fmas_f32 v83, v83, v86, v90
	v_div_fixup_f32 v82, v83, v82, v88
	v_mul_f32_e32 v82, v84, v82
	v_cvt_pk_bf16_f32 v82, v82, s0
	ds_write_b16 v168, v82 offset:17984
	v_mul_f32_e32 v82, 0xbfb8aa3b, v89
	v_exp_f32_e32 v82, v82
	s_nop 0
	v_add_f32_e32 v82, 1.0, v82
	v_div_scale_f32 v83, s[12:13], v82, v82, v89
	v_rcp_f32_e32 v84, v83
	s_nop 0
	v_fma_f32 v86, -v83, v84, 1.0
	v_fmac_f32_e32 v84, v86, v84
	v_div_scale_f32 v86, vcc, v89, v82, v89
	v_mul_f32_e32 v87, v86, v84
	v_fma_f32 v88, -v83, v87, v86
	v_fmac_f32_e32 v87, v88, v84
	v_fma_f32 v83, -v83, v87, v86
	v_div_fmas_f32 v83, v83, v84, v87
	v_div_fixup_f32 v82, v83, v82, v89
	v_mul_f32_e32 v82, v85, v82
	v_cvt_pk_bf16_f32 v82, v82, s0
	ds_write_b16 v168, v82 offset:18256
	v_mul_f32_e32 v82, 0xbfb8aa3b, v78
	v_exp_f32_e32 v82, v82
	s_nop 0
	v_add_f32_e32 v82, 1.0, v82
	v_div_scale_f32 v83, s[12:13], v82, v82, v78
	v_rcp_f32_e32 v84, v83
	s_nop 0
	v_fma_f32 v85, -v83, v84, 1.0
	v_fmac_f32_e32 v84, v85, v84
	v_div_scale_f32 v85, vcc, v78, v82, v78
	v_mul_f32_e32 v86, v85, v84
	v_fma_f32 v87, -v83, v86, v85
	v_fmac_f32_e32 v86, v87, v84
	v_fma_f32 v83, -v83, v86, v85
	v_div_fmas_f32 v83, v83, v84, v86
	v_div_fixup_f32 v78, v83, v82, v78
	v_mul_f32_e32 v74, v74, v78
	v_cvt_pk_bf16_f32 v74, v74, s0
	ds_write_b16 v168, v74 offset:21760
	v_mul_f32_e32 v74, 0xbfb8aa3b, v79
	v_exp_f32_e32 v74, v74
	s_nop 0
	v_add_f32_e32 v74, 1.0, v74
	v_div_scale_f32 v78, s[12:13], v74, v74, v79
	v_rcp_f32_e32 v82, v78
	s_nop 0
	v_fma_f32 v83, -v78, v82, 1.0
	v_fmac_f32_e32 v82, v83, v82
	v_div_scale_f32 v83, vcc, v79, v74, v79
	v_mul_f32_e32 v84, v83, v82
	v_fma_f32 v85, -v78, v84, v83
	v_fmac_f32_e32 v84, v85, v82
	v_fma_f32 v78, -v78, v84, v83
	v_div_fmas_f32 v78, v78, v82, v84
	v_div_fixup_f32 v74, v78, v74, v79
	v_mul_f32_e32 v74, v75, v74
	v_cvt_pk_bf16_f32 v74, v74, s0
	ds_write_b16 v168, v74 offset:22032
	v_mul_f32_e32 v74, 0xbfb8aa3b, v80
	v_exp_f32_e32 v74, v74
	s_nop 0
	v_add_f32_e32 v74, 1.0, v74
	v_div_scale_f32 v75, s[12:13], v74, v74, v80
	v_rcp_f32_e32 v78, v75
	s_nop 0
	v_fma_f32 v79, -v75, v78, 1.0
	v_fmac_f32_e32 v78, v79, v78
	v_div_scale_f32 v79, vcc, v80, v74, v80
	v_mul_f32_e32 v82, v79, v78
; __device__ __forceinline__ float siluf_(float x) { return x / (1.0f + __expf(-x)); }
; __device__ __forceinline__ void phase_ffn_up(const Params& p, const u16* Wgu, u16* smem, volatile LAS unsigned* vb_) {
;     ...
;     for (int i = 0; i < 8; ++i)
; #pragma unroll
;       for (int jp = 0; jp < 2; ++jp) {
; #pragma unroll
;         for (int r = 0; r < 4; ++r) {
;           const float g = acc[i][2 * jp][r], u = acc[i][2 * jp + 1][r];
;           smem[(wm * 128 + i * 16 + (lane >> 4) * 4 + r) * 136 + (wn * 2 + jp) * 16 + (lane & 15)] = f2bf(siluf_(g) * u);
;         }
;         __builtin_amdgcn_sched_barrier(0);
;       }
	v_fma_f32 v83, -v75, v82, v79
	v_fmac_f32_e32 v82, v83, v78
	v_fma_f32 v75, -v75, v82, v79
	v_div_fmas_f32 v75, v75, v78, v82
	v_div_fixup_f32 v74, v75, v74, v80
	v_mul_f32_e32 v74, v76, v74
	v_cvt_pk_bf16_f32 v74, v74, s0
	ds_write_b16 v168, v74 offset:22304
	v_mul_f32_e32 v74, 0xbfb8aa3b, v81
	v_exp_f32_e32 v74, v74
	s_nop 0
	v_add_f32_e32 v74, 1.0, v74
	v_div_scale_f32 v75, s[12:13], v74, v74, v81
	v_rcp_f32_e32 v76, v75
	s_nop 0
	v_fma_f32 v78, -v75, v76, 1.0
	v_fmac_f32_e32 v76, v78, v76
	v_div_scale_f32 v78, vcc, v81, v74, v81
	v_mul_f32_e32 v79, v78, v76
	v_fma_f32 v80, -v75, v79, v78
	v_fmac_f32_e32 v79, v80, v76
	v_fma_f32 v75, -v75, v79, v78
	v_div_fmas_f32 v75, v75, v76, v79
	v_div_fixup_f32 v74, v75, v74, v81
	v_mul_f32_e32 v74, v77, v74
	v_cvt_pk_bf16_f32 v74, v74, s0
	ds_write_b16 v168, v74 offset:22576
	v_mul_f32_e32 v74, 0xbfb8aa3b, v70
	v_exp_f32_e32 v74, v74
	s_nop 0
	v_add_f32_e32 v74, 1.0, v74
	v_div_scale_f32 v75, s[12:13], v74, v74, v70
	v_rcp_f32_e32 v76, v75
	s_nop 0
	v_fma_f32 v77, -v75, v76, 1.0
	v_fmac_f32_e32 v76, v77, v76
	v_div_scale_f32 v77, vcc, v70, v74, v70
	v_mul_f32_e32 v78, v77, v76
	v_fma_f32 v79, -v75, v78, v77
	v_fmac_f32_e32 v78, v79, v76
	v_fma_f32 v75, -v75, v78, v77
	v_div_fmas_f32 v75, v75, v76, v78
	v_div_fixup_f32 v70, v75, v74, v70
	v_mul_f32_e32 v66, v66, v70
	v_cvt_pk_bf16_f32 v66, v66, s0
	ds_write_b16 v168, v66 offset:21792
	v_mul_f32_e32 v66, 0xbfb8aa3b, v71
	v_exp_f32_e32 v66, v66
	s_nop 0
	v_add_f32_e32 v66, 1.0, v66
	v_div_scale_f32 v70, s[12:13], v66, v66, v71
	v_rcp_f32_e32 v74, v70
	s_nop 0
	v_fma_f32 v75, -v70, v74, 1.0
	v_fmac_f32_e32 v74, v75, v74
	v_div_scale_f32 v75, vcc, v71, v66, v71
	v_mul_f32_e32 v76, v75, v74
	v_fma_f32 v77, -v70, v76, v75
	v_fmac_f32_e32 v76, v77, v74
	v_fma_f32 v70, -v70, v76, v75
	v_div_fmas_f32 v70, v70, v74, v76
	v_div_fixup_f32 v66, v70, v66, v71
	v_mul_f32_e32 v66, v67, v66
	v_cvt_pk_bf16_f32 v66, v66, s0
	ds_write_b16 v168, v66 offset:22064
	v_mul_f32_e32 v66, 0xbfb8aa3b, v72
	v_exp_f32_e32 v66, v66
	s_nop 0
	v_add_f32_e32 v66, 1.0, v66
	v_div_scale_f32 v67, s[12:13], v66, v66, v72
	v_rcp_f32_e32 v70, v67
	s_nop 0
	v_fma_f32 v71, -v67, v70, 1.0
	v_fmac_f32_e32 v70, v71, v70
	v_div_scale_f32 v71, vcc, v72, v66, v72
	v_mul_f32_e32 v74, v71, v70
	v_fma_f32 v75, -v67, v74, v71
	v_fmac_f32_e32 v74, v75, v70
	v_fma_f32 v67, -v67, v74, v71
	v_div_fmas_f32 v67, v67, v70, v74
	v_div_fixup_f32 v66, v67, v66, v72
	v_mul_f32_e32 v66, v68, v66
	v_cvt_pk_bf16_f32 v66, v66, s0
	ds_write_b16 v168, v66 offset:22336
	v_mul_f32_e32 v66, 0xbfb8aa3b, v73
	v_exp_f32_e32 v66, v66
	s_nop 0
	v_add_f32_e32 v66, 1.0, v66
	v_div_scale_f32 v67, s[12:13], v66, v66, v73
	v_rcp_f32_e32 v68, v67
	s_nop 0
	v_fma_f32 v70, -v67, v68, 1.0
	v_fmac_f32_e32 v68, v70, v68
	v_div_scale_f32 v70, vcc, v73, v66, v73
	v_mul_f32_e32 v71, v70, v68
	v_fma_f32 v72, -v67, v71, v70
	v_fmac_f32_e32 v71, v72, v68
	v_fma_f32 v67, -v67, v71, v70
	v_div_fmas_f32 v67, v67, v68, v71
	v_div_fixup_f32 v66, v67, v66, v73
	v_mul_f32_e32 v66, v69, v66
	v_cvt_pk_bf16_f32 v66, v66, s0
	ds_write_b16 v168, v66 offset:22608
	v_mul_f32_e32 v66, 0xbfb8aa3b, v62
	v_exp_f32_e32 v66, v66
	s_nop 0
	v_add_f32_e32 v66, 1.0, v66
	v_div_scale_f32 v67, s[12:13], v66, v66, v62
	v_rcp_f32_e32 v68, v67
	s_nop 0
	v_fma_f32 v69, -v67, v68, 1.0
	v_fmac_f32_e32 v68, v69, v68
	v_div_scale_f32 v69, vcc, v62, v66, v62
	v_mul_f32_e32 v70, v69, v68
	v_fma_f32 v71, -v67, v70, v69
	v_fmac_f32_e32 v70, v71, v68
	v_fma_f32 v67, -v67, v70, v69
	v_div_fmas_f32 v67, v67, v68, v70
	v_div_fixup_f32 v62, v67, v66, v62
	v_mul_f32_e32 v58, v58, v62
	v_cvt_pk_bf16_f32 v58, v58, s0
	ds_write_b16 v168, v58 offset:26112
	v_mul_f32_e32 v58, 0xbfb8aa3b, v63
	v_exp_f32_e32 v58, v58
	s_nop 0
	v_add_f32_e32 v58, 1.0, v58
	v_div_scale_f32 v62, s[12:13], v58, v58, v63
	v_rcp_f32_e32 v66, v62
	s_nop 0
	v_fma_f32 v67, -v62, v66, 1.0
	v_fmac_f32_e32 v66, v67, v66
	v_div_scale_f32 v67, vcc, v63, v58, v63
	v_mul_f32_e32 v68, v67, v66
	v_fma_f32 v69, -v62, v68, v67
	v_fmac_f32_e32 v68, v69, v66
	v_fma_f32 v62, -v62, v68, v67
	v_div_fmas_f32 v62, v62, v66, v68
	v_div_fixup_f32 v58, v62, v58, v63
	v_mul_f32_e32 v58, v59, v58
	v_cvt_pk_bf16_f32 v58, v58, s0
	ds_write_b16 v168, v58 offset:26384
	v_mul_f32_e32 v58, 0xbfb8aa3b, v64
	v_exp_f32_e32 v58, v58
	s_nop 0
	v_add_f32_e32 v58, 1.0, v58
	v_div_scale_f32 v59, s[12:13], v58, v58, v64
	v_rcp_f32_e32 v62, v59
	s_nop 0
	v_fma_f32 v63, -v59, v62, 1.0
	v_fmac_f32_e32 v62, v63, v62
	v_div_scale_f32 v63, vcc, v64, v58, v64
	v_mul_f32_e32 v66, v63, v62
	v_fma_f32 v67, -v59, v66, v63
	v_fmac_f32_e32 v66, v67, v62
	v_fma_f32 v59, -v59, v66, v63
	v_div_fmas_f32 v59, v59, v62, v66
	v_div_fixup_f32 v58, v59, v58, v64
	v_mul_f32_e32 v58, v60, v58
	v_cvt_pk_bf16_f32 v58, v58, s0
	ds_write_b16 v168, v58 offset:26656
	v_mul_f32_e32 v58, 0xbfb8aa3b, v65
	v_exp_f32_e32 v58, v58
	s_nop 0
	v_add_f32_e32 v58, 1.0, v58
	v_div_scale_f32 v59, s[12:13], v58, v58, v65
	v_rcp_f32_e32 v60, v59
	s_nop 0
	v_fma_f32 v62, -v59, v60, 1.0
	v_fmac_f32_e32 v60, v62, v60
	v_div_scale_f32 v62, vcc, v65, v58, v65
	v_mul_f32_e32 v63, v62, v60
	v_fma_f32 v64, -v59, v63, v62
	v_fmac_f32_e32 v63, v64, v60
	v_fma_f32 v59, -v59, v63, v62
	v_div_fmas_f32 v59, v59, v60, v63
	v_div_fixup_f32 v58, v59, v58, v65
	v_mul_f32_e32 v58, v61, v58
	v_cvt_pk_bf16_f32 v58, v58, s0
	ds_write_b16 v168, v58 offset:26928
	v_mul_f32_e32 v58, 0xbfb8aa3b, v54
	v_exp_f32_e32 v58, v58
	s_nop 0
	v_add_f32_e32 v58, 1.0, v58
	v_div_scale_f32 v59, s[12:13], v58, v58, v54
	v_rcp_f32_e32 v60, v59
	s_nop 0
	v_fma_f32 v61, -v59, v60, 1.0
	v_fmac_f32_e32 v60, v61, v60
; __device__ __forceinline__ float siluf_(float x) { return x / (1.0f + __expf(-x)); }
; __device__ __forceinline__ void phase_ffn_up(const Params& p, const u16* Wgu, u16* smem, volatile LAS unsigned* vb_) {
;     ...
;     for (int i = 0; i < 8; ++i)
; #pragma unroll
;       for (int jp = 0; jp < 2; ++jp) {
; #pragma unroll
;         for (int r = 0; r < 4; ++r) {
;           const float g = acc[i][2 * jp][r], u = acc[i][2 * jp + 1][r];
;           smem[(wm * 128 + i * 16 + (lane >> 4) * 4 + r) * 136 + (wn * 2 + jp) * 16 + (lane & 15)] = f2bf(siluf_(g) * u);
;         }
;         __builtin_amdgcn_sched_barrier(0);
;       }
;     __syncthreads();
	v_div_scale_f32 v61, vcc, v54, v58, v54
	v_mul_f32_e32 v62, v61, v60
	v_fma_f32 v63, -v59, v62, v61
	v_fmac_f32_e32 v62, v63, v60
	v_fma_f32 v59, -v59, v62, v61
	v_div_fmas_f32 v59, v59, v60, v62
	v_div_fixup_f32 v54, v59, v58, v54
	v_mul_f32_e32 v50, v50, v54
	v_cvt_pk_bf16_f32 v50, v50, s0
	ds_write_b16 v168, v50 offset:26144
	v_mul_f32_e32 v50, 0xbfb8aa3b, v55
	v_exp_f32_e32 v50, v50
	s_nop 0
	v_add_f32_e32 v50, 1.0, v50
	v_div_scale_f32 v54, s[12:13], v50, v50, v55
	v_rcp_f32_e32 v58, v54
	s_nop 0
	v_fma_f32 v59, -v54, v58, 1.0
	v_fmac_f32_e32 v58, v59, v58
	v_div_scale_f32 v59, vcc, v55, v50, v55
	v_mul_f32_e32 v60, v59, v58
	v_fma_f32 v61, -v54, v60, v59
	v_fmac_f32_e32 v60, v61, v58
	v_fma_f32 v54, -v54, v60, v59
	v_div_fmas_f32 v54, v54, v58, v60
	v_div_fixup_f32 v50, v54, v50, v55
	v_mul_f32_e32 v50, v51, v50
	v_cvt_pk_bf16_f32 v50, v50, s0
	ds_write_b16 v168, v50 offset:26416
	v_mul_f32_e32 v50, 0xbfb8aa3b, v56
	v_exp_f32_e32 v50, v50
	s_nop 0
	v_add_f32_e32 v50, 1.0, v50
	v_div_scale_f32 v51, s[12:13], v50, v50, v56
	v_rcp_f32_e32 v54, v51
	s_nop 0
	v_fma_f32 v55, -v51, v54, 1.0
	v_fmac_f32_e32 v54, v55, v54
	v_div_scale_f32 v55, vcc, v56, v50, v56
	v_mul_f32_e32 v58, v55, v54
	v_fma_f32 v59, -v51, v58, v55
	v_fmac_f32_e32 v58, v59, v54
	v_fma_f32 v51, -v51, v58, v55
	v_div_fmas_f32 v51, v51, v54, v58
	v_div_fixup_f32 v50, v51, v50, v56
	v_mul_f32_e32 v50, v52, v50
	v_cvt_pk_bf16_f32 v50, v50, s0
	ds_write_b16 v168, v50 offset:26688
	v_mul_f32_e32 v50, 0xbfb8aa3b, v57
	v_exp_f32_e32 v50, v50
	s_nop 0
	v_add_f32_e32 v50, 1.0, v50
	v_div_scale_f32 v51, s[12:13], v50, v50, v57
	v_rcp_f32_e32 v52, v51
	s_nop 0
	v_fma_f32 v54, -v51, v52, 1.0
	v_fmac_f32_e32 v52, v54, v52
	v_div_scale_f32 v54, vcc, v57, v50, v57
	v_mul_f32_e32 v55, v54, v52
	v_fma_f32 v56, -v51, v55, v54
	v_fmac_f32_e32 v55, v56, v52
	v_fma_f32 v51, -v51, v55, v54
	v_div_fmas_f32 v51, v51, v52, v55
	v_div_fixup_f32 v50, v51, v50, v57
	v_mul_f32_e32 v50, v53, v50
	v_cvt_pk_bf16_f32 v50, v50, s0
	ds_write_b16 v168, v50 offset:26960
	v_mul_f32_e32 v50, 0xbfb8aa3b, v46
	v_exp_f32_e32 v50, v50
	s_nop 0
	v_add_f32_e32 v50, 1.0, v50
	v_div_scale_f32 v51, s[12:13], v50, v50, v46
	v_rcp_f32_e32 v52, v51
	s_nop 0
	v_fma_f32 v53, -v51, v52, 1.0
	v_fmac_f32_e32 v52, v53, v52
	v_div_scale_f32 v53, vcc, v46, v50, v46
	v_mul_f32_e32 v54, v53, v52
	v_fma_f32 v55, -v51, v54, v53
	v_fmac_f32_e32 v54, v55, v52
	v_fma_f32 v51, -v51, v54, v53
	v_div_fmas_f32 v51, v51, v52, v54
	v_div_fixup_f32 v46, v51, v50, v46
	v_mul_f32_e32 v42, v42, v46
	v_cvt_pk_bf16_f32 v42, v42, s0
	ds_write_b16 v168, v42 offset:30464
	v_mul_f32_e32 v42, 0xbfb8aa3b, v47
	v_exp_f32_e32 v42, v42
	s_nop 0
	v_add_f32_e32 v42, 1.0, v42
	v_div_scale_f32 v46, s[12:13], v42, v42, v47
	v_rcp_f32_e32 v50, v46
	s_nop 0
	v_fma_f32 v51, -v46, v50, 1.0
	v_fmac_f32_e32 v50, v51, v50
	v_div_scale_f32 v51, vcc, v47, v42, v47
	v_mul_f32_e32 v52, v51, v50
	v_fma_f32 v53, -v46, v52, v51
	v_fmac_f32_e32 v52, v53, v50
	v_fma_f32 v46, -v46, v52, v51
	v_div_fmas_f32 v46, v46, v50, v52
	v_div_fixup_f32 v42, v46, v42, v47
	v_mul_f32_e32 v42, v43, v42
	v_cvt_pk_bf16_f32 v42, v42, s0
	ds_write_b16 v168, v42 offset:30736
	v_mul_f32_e32 v42, 0xbfb8aa3b, v48
	v_exp_f32_e32 v42, v42
	s_nop 0
	v_add_f32_e32 v42, 1.0, v42
	v_div_scale_f32 v43, s[12:13], v42, v42, v48
	v_rcp_f32_e32 v46, v43
	s_nop 0
	v_fma_f32 v47, -v43, v46, 1.0
	v_fmac_f32_e32 v46, v47, v46
	v_div_scale_f32 v47, vcc, v48, v42, v48
	v_mul_f32_e32 v50, v47, v46
	v_fma_f32 v51, -v43, v50, v47
	v_fmac_f32_e32 v50, v51, v46
	v_fma_f32 v43, -v43, v50, v47
	v_div_fmas_f32 v43, v43, v46, v50
	v_div_fixup_f32 v42, v43, v42, v48
	v_mul_f32_e32 v42, v44, v42
	v_cvt_pk_bf16_f32 v42, v42, s0
	ds_write_b16 v168, v42 offset:31008
	v_mul_f32_e32 v42, 0xbfb8aa3b, v49
	v_exp_f32_e32 v42, v42
	s_nop 0
	v_add_f32_e32 v42, 1.0, v42
	v_div_scale_f32 v43, s[12:13], v42, v42, v49
	v_rcp_f32_e32 v44, v43
	s_nop 0
	v_fma_f32 v46, -v43, v44, 1.0
	v_fmac_f32_e32 v44, v46, v44
	v_div_scale_f32 v46, vcc, v49, v42, v49
	v_mul_f32_e32 v47, v46, v44
	v_fma_f32 v48, -v43, v47, v46
	v_fmac_f32_e32 v47, v48, v44
	v_fma_f32 v43, -v43, v47, v46
	v_div_fmas_f32 v43, v43, v44, v47
	v_div_fixup_f32 v42, v43, v42, v49
	v_mul_f32_e32 v42, v45, v42
	v_cvt_pk_bf16_f32 v42, v42, s0
	ds_write_b16 v168, v42 offset:31280
	v_mul_f32_e32 v42, 0xbfb8aa3b, v38
	v_exp_f32_e32 v42, v42
	s_nop 0
	v_add_f32_e32 v42, 1.0, v42
	v_div_scale_f32 v43, s[12:13], v42, v42, v38
	v_rcp_f32_e32 v44, v43
	s_nop 0
	v_fma_f32 v45, -v43, v44, 1.0
	v_fmac_f32_e32 v44, v45, v44
	v_div_scale_f32 v45, vcc, v38, v42, v38
	v_mul_f32_e32 v46, v45, v44
	v_fma_f32 v47, -v43, v46, v45
	v_fmac_f32_e32 v46, v47, v44
	v_fma_f32 v43, -v43, v46, v45
	v_div_fmas_f32 v43, v43, v44, v46
	v_div_fixup_f32 v38, v43, v42, v38
	v_mul_f32_e32 v34, v34, v38
	v_cvt_pk_bf16_f32 v34, v34, s0
	ds_write_b16 v168, v34 offset:30496
	v_mul_f32_e32 v34, 0xbfb8aa3b, v39
	v_exp_f32_e32 v34, v34
	s_nop 0
	v_add_f32_e32 v34, 1.0, v34
	v_div_scale_f32 v38, s[12:13], v34, v34, v39
	v_rcp_f32_e32 v42, v38
	s_nop 0
	v_fma_f32 v43, -v38, v42, 1.0
	v_fmac_f32_e32 v42, v43, v42
	v_div_scale_f32 v43, vcc, v39, v34, v39
	v_mul_f32_e32 v44, v43, v42
	v_fma_f32 v45, -v38, v44, v43
	v_fmac_f32_e32 v44, v45, v42
	v_fma_f32 v38, -v38, v44, v43
	v_div_fmas_f32 v38, v38, v42, v44
	v_div_fixup_f32 v34, v38, v34, v39
	v_mul_f32_e32 v34, v35, v34
	v_cvt_pk_bf16_f32 v34, v34, s0
	ds_write_b16 v168, v34 offset:30768
	v_mul_f32_e32 v34, 0xbfb8aa3b, v40
	v_exp_f32_e32 v34, v34
	s_nop 0
	v_add_f32_e32 v34, 1.0, v34
	v_div_scale_f32 v35, s[12:13], v34, v34, v40
	v_rcp_f32_e32 v38, v35
	s_nop 0
	v_fma_f32 v39, -v35, v38, 1.0
	v_fmac_f32_e32 v38, v39, v38
	v_div_scale_f32 v39, vcc, v40, v34, v40
	v_mul_f32_e32 v42, v39, v38
	v_fma_f32 v43, -v35, v42, v39
	v_fmac_f32_e32 v42, v43, v38
	v_fma_f32 v35, -v35, v42, v39
	v_div_fmas_f32 v35, v35, v38, v42
	v_div_fixup_f32 v34, v35, v34, v40
	v_mul_f32_e32 v34, v36, v34
	v_cvt_pk_bf16_f32 v34, v34, s0
	ds_write_b16 v168, v34 offset:31040
	v_mul_f32_e32 v34, 0xbfb8aa3b, v41
	v_exp_f32_e32 v34, v34
	s_nop 0
	v_add_f32_e32 v34, 1.0, v34
	v_div_scale_f32 v35, s[12:13], v34, v34, v41
	v_rcp_f32_e32 v36, v35
	s_nop 0
	v_fma_f32 v38, -v35, v36, 1.0
	v_fmac_f32_e32 v36, v38, v36
	v_div_scale_f32 v38, vcc, v41, v34, v41
	v_mul_f32_e32 v39, v38, v36
	v_fma_f32 v40, -v35, v39, v38
	v_fmac_f32_e32 v39, v40, v36
	v_fma_f32 v35, -v35, v39, v38
	v_div_fmas_f32 v35, v35, v36, v39
	v_div_fixup_f32 v34, v35, v34, v41
	v_mul_f32_e32 v34, v37, v34
	v_cvt_pk_bf16_f32 v34, v34, s0
	ds_write_b16 v168, v34 offset:31312
	s_waitcnt lgkmcnt(0)
	s_barrier
; __device__ __forceinline__ void phase_ffn_up(const Params& p, const u16* Wgu, u16* smem, volatile LAS unsigned* vb_) {
;     ...
;     __syncthreads();
; #pragma unroll
;     for (int k = 0; k < 8; ++k) {
;       const int c = tid + 512 * k;
;       const int row = c >> 4, ch = c & 15;
;       const uint4 v = *(const uint4*)(smem + row * 136 + ch * 8);
;       *(uint4*)(act + (size_t)(mt * 256 + row) * DFF + nt * 128 + ch * 8) = v;
;     }
;     __syncthreads();
	ds_read_b128 v[34:37], v197
	s_lshl_b32 s12, s40, 7
	s_ashr_i32 s13, s12, 31
	v_lshl_add_u64 v[38:39], s[12:13], 1, v[166:167]
	v_add_u32_e32 v40, s39, v189
	v_mad_i64_i32 v[40:41], s[12:13], v40, s7, v[38:39]
	s_waitcnt lgkmcnt(0)
	global_store_dwordx4 v[40:41], v[34:37], off
	ds_read_b128 v[34:37], v198
	v_add_u32_e32 v40, s39, v169
	v_mad_i64_i32 v[40:41], s[12:13], v40, s7, v[38:39]
	s_and_b64 vcc, exec, s[10:11]
	s_waitcnt lgkmcnt(0)
	global_store_dwordx4 v[40:41], v[34:37], off
	ds_read_b128 v[34:37], v199
	v_add_u32_e32 v40, s39, v190
	v_mad_i64_i32 v[40:41], s[12:13], v40, s7, v[38:39]
	s_mov_b32 s20, s41
	s_waitcnt lgkmcnt(0)
	global_store_dwordx4 v[40:41], v[34:37], off
	ds_read_b128 v[34:37], v200
	v_add_u32_e32 v40, s39, v191
	v_mad_i64_i32 v[40:41], s[12:13], v40, s7, v[38:39]
	s_waitcnt lgkmcnt(0)
	global_store_dwordx4 v[40:41], v[34:37], off
	ds_read_b128 v[34:37], v204
	v_add_u32_e32 v40, s39, v192
	v_mad_i64_i32 v[40:41], s[12:13], v40, s7, v[38:39]
	s_waitcnt lgkmcnt(0)
	global_store_dwordx4 v[40:41], v[34:37], off
	ds_read_b128 v[34:37], v205
	v_add_u32_e32 v40, s39, v193
	v_mad_i64_i32 v[40:41], s[12:13], v40, s7, v[38:39]
	s_waitcnt lgkmcnt(0)
	global_store_dwordx4 v[40:41], v[34:37], off
	ds_read_b128 v[34:37], v206
	v_add_u32_e32 v40, s39, v194
	v_mad_i64_i32 v[40:41], s[12:13], v40, s7, v[38:39]
	s_waitcnt lgkmcnt(0)
	global_store_dwordx4 v[40:41], v[34:37], off
	ds_read_b128 v[34:37], v207
	v_add_u32_e32 v40, s39, v195
	v_mad_i64_i32 v[38:39], s[12:13], v40, s7, v[38:39]
	s_mov_b64 s[12:13], -1
	s_waitcnt lgkmcnt(0)
	global_store_dwordx4 v[38:39], v[34:37], off
	s_barrier
	s_cbranch_vccz .LBB0_598
